# v109 + W_down conversion loop unrolled x2, two load sets, copies behind vmcnt(40) (previous stores may stay in flight)
# speedup vs baseline: 1.0027x; 1.0027x over previous
; #define LDS_WAIT() asm volatile("s_waitcnt lgkmcnt(0)" ::: "memory")
; __device__ __forceinline__ void transpose_items_pipe(const float* W, int K, int ldw, int src0, int ncols, int blk, int mul, int add, bf16* WT, LAS float* scr, int gw, int NGW, int lane) {
;     ...
;         const int kb = it / nblk, nb = it - kb * nblk, k0 = 64 * kb, nl = 32 * nb;
;         const int drow = (nl / blk) * mul + (nl % blk) + add;
;         const int nit = it + NGW; const bool more = nit < nitems;
;         float nv[32];
;         { const int ld = more ? nit : it;
;           const int kb2 = ld / nblk, nb2 = ld - kb2 * nblk; const float* src = W + (size_t)(64 * kb2) * ldw + src0 + 32 * nb2 + (lane & 31);
; #pragma unroll
;           for (int i = 0; i < 32; ++i) nv[i] = src[(size_t)(2 * i + (lane >> 5)) * ldw]; }
;         asm volatile("" ::: "memory");
; #pragma unroll
;         for (int i = 0; i < 32; ++i) scr[(2 * i + (lane >> 5)) * 33 + (lane & 31)] = tv[i];
;         LDS_WAIT(); asm volatile("" ::: "memory");
.Lwd_X:
	s_add_i32 s9, s6, 0xfffffc00
	s_ashr_i32 s0, s9, 31
	s_lshr_b32 s0, s0, 25
	s_add_i32 s0, s9, s0
	s_ashr_i32 s12, s0, 7
	s_lshl_b32 s0, s12, 12
	s_sub_i32 s13, s7, s0
	s_cmpk_lt_i32 s9, 0x5200
	s_cselect_b64 s[0:1], -1, 0
	s_and_b64 vcc, s[0:1], exec
	s_add_i32 s32, s6, 0x400
	s_cmpk_lt_i32 s9, 0x4e00
	s_cselect_b32 s9, s32, s9
	s_ashr_i32 s0, s9, 31
	s_lshr_b32 s0, s0, 25
	s_add_i32 s0, s9, s0
	s_ashr_i32 s10, s0, 7
	s_lshl_b32 s0, s10, 6
	s_ashr_i32 s1, s0, 31
	s_lshl_b64 s[0:1], s[0:1], 14
	s_add_u32 s11, s60, s0
	s_addc_u32 s14, s61, s1
	s_lshl_b32 s0, s10, 12
	s_lshl_b32 s1, s9, 5
	s_sub_i32 s0, s1, s0
	s_ashr_i32 s1, s0, 31
	s_lshl_b64 s[0:1], s[0:1], 2
	s_add_u32 s10, s11, s0
	s_addc_u32 s11, s14, s1
	v_mov_b32_e32 v7, v3
	v_lshl_add_u64 v[108:109], s[10:11], 0, v[2:3]
	v_mov_b32_e32 v9, v3
	v_mov_b32_e32 v11, v3
	v_mov_b32_e32 v13, v3
	v_mov_b32_e32 v15, v3
	v_mov_b32_e32 v17, v3
	v_mov_b32_e32 v19, v3
	v_mov_b32_e32 v21, v3
	v_mov_b32_e32 v23, v3
	v_mov_b32_e32 v25, v3
	v_mov_b32_e32 v27, v3
	v_mov_b32_e32 v29, v3
	v_mov_b32_e32 v31, v3
	v_mov_b32_e32 v33, v3
	v_mov_b32_e32 v35, v3
	v_mov_b32_e32 v37, v3
	v_mov_b32_e32 v39, v3
	v_mov_b32_e32 v41, v3
	v_mov_b32_e32 v43, v3
	v_mov_b32_e32 v45, v3
	v_mov_b32_e32 v47, v3
	v_mov_b32_e32 v49, v3
	v_mov_b32_e32 v51, v3
	v_mov_b32_e32 v53, v3
	v_mov_b32_e32 v55, v3
	v_mov_b32_e32 v57, v3
	v_mov_b32_e32 v59, v3
	v_mov_b32_e32 v61, v3
	v_mov_b32_e32 v63, v3
	v_mov_b32_e32 v65, v3
	v_mov_b32_e32 v67, v3
	v_mov_b32_e32 v69, v3
	v_lshl_add_u64 v[110:111], v[108:109], 0, v[6:7]
	v_lshl_add_u64 v[112:113], v[108:109], 0, v[8:9]
	v_lshl_add_u64 v[114:115], v[108:109], 0, v[10:11]
	v_lshl_add_u64 v[116:117], v[108:109], 0, v[12:13]
	v_lshl_add_u64 v[118:119], v[108:109], 0, v[14:15]
	v_lshl_add_u64 v[120:121], v[108:109], 0, v[16:17]
	v_lshl_add_u64 v[122:123], v[108:109], 0, v[18:19]
	v_lshl_add_u64 v[124:125], v[108:109], 0, v[20:21]
	v_lshl_add_u64 v[126:127], v[108:109], 0, v[22:23]
	v_lshl_add_u64 v[128:129], v[108:109], 0, v[24:25]
	v_lshl_add_u64 v[130:131], v[108:109], 0, v[26:27]
	v_lshl_add_u64 v[132:133], v[108:109], 0, v[28:29]
	v_lshl_add_u64 v[134:135], v[108:109], 0, v[30:31]
	v_lshl_add_u64 v[136:137], v[108:109], 0, v[32:33]
	v_lshl_add_u64 v[138:139], v[108:109], 0, v[34:35]
	v_lshl_add_u64 v[140:141], v[108:109], 0, v[36:37]
	v_lshl_add_u64 v[142:143], v[108:109], 0, v[38:39]
	v_lshl_add_u64 v[144:145], v[108:109], 0, v[40:41]
	v_lshl_add_u64 v[146:147], v[108:109], 0, v[42:43]
	v_lshl_add_u64 v[148:149], v[108:109], 0, v[44:45]
	v_lshl_add_u64 v[150:151], v[108:109], 0, v[46:47]
	v_lshl_add_u64 v[152:153], v[108:109], 0, v[48:49]
	v_lshl_add_u64 v[154:155], v[108:109], 0, v[50:51]
	v_lshl_add_u64 v[156:157], v[108:109], 0, v[52:53]
	v_lshl_add_u64 v[158:159], v[108:109], 0, v[54:55]
	v_lshl_add_u64 v[160:161], v[108:109], 0, v[56:57]
	v_lshl_add_u64 v[162:163], v[108:109], 0, v[58:59]
	v_lshl_add_u64 v[164:165], v[108:109], 0, v[60:61]
	v_lshl_add_u64 v[166:167], v[108:109], 0, v[62:63]
	v_lshl_add_u64 v[168:169], v[108:109], 0, v[64:65]
	v_lshl_add_u64 v[170:171], v[108:109], 0, v[66:67]
	v_lshl_add_u64 v[108:109], v[108:109], 0, v[68:69]
	global_load_dword v7, v[110:111], off
	global_load_dword v9, v[112:113], off
	global_load_dword v11, v[114:115], off
	global_load_dword v13, v[116:117], off
	global_load_dword v15, v[118:119], off
	global_load_dword v17, v[120:121], off
	global_load_dword v19, v[122:123], off
	global_load_dword v21, v[124:125], off
	global_load_dword v23, v[126:127], off
	global_load_dword v25, v[128:129], off
	global_load_dword v27, v[130:131], off
	global_load_dword v29, v[132:133], off
	global_load_dword v31, v[134:135], off
	global_load_dword v33, v[136:137], off
	global_load_dword v35, v[138:139], off
	global_load_dword v37, v[140:141], off
	global_load_dword v39, v[158:159], off
	global_load_dword v41, v[160:161], off
	global_load_dword v43, v[162:163], off
	global_load_dword v45, v[164:165], off
	global_load_dword v47, v[166:167], off
	global_load_dword v49, v[168:169], off
	global_load_dword v51, v[170:171], off
	global_load_dword v53, v[108:109], off
	global_load_dword v55, v[142:143], off
	global_load_dword v57, v[144:145], off
	global_load_dword v59, v[146:147], off
	global_load_dword v61, v[148:149], off
	global_load_dword v63, v[150:151], off
	global_load_dword v65, v[152:153], off
	global_load_dword v67, v[154:155], off
	global_load_dword v69, v[156:157], off
	v_add_u32_e32 v107, 0x400, v106
	v_add_u32_e32 v174, 0x800, v106
	v_add_u32_e32 v175, 0xc00, v106
	v_add_u32_e32 v176, 0x1000, v106
	v_add_u32_e32 v177, 0x1400, v106
	v_add_u32_e32 v178, 0x1800, v106
	v_add_u32_e32 v179, 0x1c00, v106
	ds_write2_b32 v106, v76, v75 offset1:66
	ds_write2_b32 v106, v74, v73 offset0:132 offset1:198
	ds_write2_b32 v107, v72, v71 offset0:8 offset1:74
	ds_write2_b32 v107, v70, v1 offset0:140 offset1:206
	ds_write2_b32 v174, v84, v83 offset0:16 offset1:82
	ds_write2_b32 v174, v82, v81 offset0:148 offset1:214
	ds_write2_b32 v175, v80, v79 offset0:24 offset1:90
	ds_write2_b32 v175, v78, v77 offset0:156 offset1:222
	ds_write2_b32 v176, v92, v91 offset0:32 offset1:98
	ds_write2_b32 v176, v90, v89 offset0:164 offset1:230
	ds_write2_b32 v177, v88, v87 offset0:40 offset1:106
	ds_write2_b32 v177, v86, v85 offset0:172 offset1:238
	ds_write2_b32 v178, v105, v104 offset0:48 offset1:114
	ds_write2_b32 v178, v103, v102 offset0:180 offset1:246
	ds_write2_b32 v179, v101, v100 offset0:56 offset1:122
	ds_write2_b32 v179, v99, v98 offset0:188 offset1:254
	s_waitcnt lgkmcnt(0)
; #define LAS __attribute__((address_space(3)))
; #define LDS_WAIT() asm volatile("s_waitcnt lgkmcnt(0)" ::: "memory")
; __device__ __forceinline__ unsigned pk2(float lo, float hi) { const f32x2c v = {lo, hi}; return __builtin_bit_cast(unsigned, __builtin_convertvector(v, bf16x2c)); }
; __device__ __forceinline__ void transpose_items_pipe(const float* W, int K, int ldw, int src0, int ncols, int blk, int mul, int add, bf16* WT, LAS float* scr, int gw, int NGW, int lane) {
;     ...
;         const int kb = it / nblk, nb = it - kb * nblk, k0 = 64 * kb, nl = 32 * nb;
;         const int drow = (nl / blk) * mul + (nl % blk) + add;
;         const int nit = it + NGW; const bool more = nit < nitems;
;         float nv[32];
;         { const int ld = more ? nit : it;
;           const int kb2 = ld / nblk, nb2 = ld - kb2 * nblk; const float* src = W + (size_t)(64 * kb2) * ldw + src0 + 32 * nb2 + (lane & 31);
; #pragma unroll
;           for (int i = 0; i < 32; ++i) nv[i] = src[(size_t)(2 * i + (lane >> 5)) * ldw]; }
;     ...
;         const int c = lane & 7;
; #pragma unroll
;         for (int j = 0; j < 4; ++j) { const int n = (lane >> 3) + 8 * j; const LAS float* s = scr + (8 * c) * 33 + n;
;             v4u o; o.x = pk2(s[0 * 33], s[1 * 33]); o.y = pk2(s[2 * 33], s[3 * 33]); o.z = pk2(s[4 * 33], s[5 * 33]); o.w = pk2(s[6 * 33], s[7 * 33]);
;             *(v4u*)(WT + (size_t)(drow + n) * K + k0 + 8 * c) = o; }
;         LDS_WAIT(); asm volatile("" ::: "memory");
;         if (!more) break;
; #pragma unroll
;         for (int i = 0; i < 32; ++i) tv[i] = nv[i];
;         it = nit;
	s_ashr_i32 s1, s13, 31
	s_lshl_b32 s0, s12, 6
	s_lshr_b32 s9, s1, 2
	ds_read2_b32 v[74:75], v94 offset0:33 offset1:41
	ds_read2_b32 v[76:77], v94 offset1:8
	ds_read2_b32 v[78:79], v94 offset0:66 offset1:74
	ds_read2_b32 v[80:81], v94 offset0:99 offset1:107
	ds_read2_b32 v[82:83], v94 offset0:132 offset1:140
	ds_read2_b32 v[84:85], v94 offset0:165 offset1:173
	ds_read2_b32 v[86:87], v94 offset0:198 offset1:206
	ds_read2_b32 v[88:89], v94 offset0:231 offset1:239
	s_ashr_i32 s1, s0, 31
	s_add_i32 s9, s13, s9
	ds_read2_b32 v[100:101], v94 offset0:49 offset1:57
	ds_read2_b32 v[102:103], v94 offset0:16 offset1:24
	ds_read2_b32 v[104:105], v94 offset0:82 offset1:90
	ds_read2_b32 v[108:109], v94 offset0:115 offset1:123
	ds_read2_b32 v[110:111], v94 offset0:148 offset1:156
	ds_read2_b32 v[112:113], v94 offset0:181 offset1:189
	ds_read2_b32 v[114:115], v94 offset0:214 offset1:222
	ds_read2_b32 v[116:117], v94 offset0:247 offset1:255
	v_lshl_add_u64 v[172:173], s[0:1], 1, v[4:5]
	s_and_b32 s0, s9, -2.0
	s_sub_i32 s0, s13, s0
	v_or_b32_e32 v1, s0, v93
	v_or_b32_e32 v70, s0, v95
	v_or_b32_e32 v71, s0, v96
	v_or_b32_e32 v72, s0, v97
	v_mad_i64_i32 v[90:91], s[0:1], v1, s8, v[172:173]
	v_mad_i64_i32 v[98:99], s[0:1], v70, s8, v[172:173]
	v_mad_i64_i32 v[118:119], s[0:1], v71, s8, v[172:173]
	v_mad_i64_i32 v[120:121], s[0:1], v72, s8, v[172:173]
	s_waitcnt lgkmcnt(14)
	v_cvt_pk_bf16_f32 v70, v76, v74
	s_waitcnt lgkmcnt(12)
	v_cvt_pk_bf16_f32 v71, v78, v80
	s_waitcnt lgkmcnt(10)
	v_cvt_pk_bf16_f32 v72, v82, v84
	s_waitcnt lgkmcnt(8)
	v_cvt_pk_bf16_f32 v73, v86, v88
	v_cvt_pk_bf16_f32 v74, v77, v75
	v_cvt_pk_bf16_f32 v75, v79, v81
	v_cvt_pk_bf16_f32 v76, v83, v85
	v_cvt_pk_bf16_f32 v77, v87, v89
	s_waitcnt lgkmcnt(6)
	v_cvt_pk_bf16_f32 v78, v102, v100
	s_waitcnt lgkmcnt(4)
	v_cvt_pk_bf16_f32 v79, v104, v108
	s_waitcnt lgkmcnt(2)
	v_cvt_pk_bf16_f32 v80, v110, v112
	s_waitcnt lgkmcnt(0)
	v_cvt_pk_bf16_f32 v81, v114, v116
	v_cvt_pk_bf16_f32 v82, v103, v101
	v_cvt_pk_bf16_f32 v83, v105, v109
	v_cvt_pk_bf16_f32 v84, v111, v113
	v_cvt_pk_bf16_f32 v85, v115, v117
	global_store_dwordx4 v[90:91], v[70:73], off
	global_store_dwordx4 v[98:99], v[74:77], off
	global_store_dwordx4 v[118:119], v[78:81], off
	global_store_dwordx4 v[120:121], v[82:85], off
	s_waitcnt lgkmcnt(0)
	s_addk_i32 s6, 0x400
	s_add_i32 s7, s7, 0x8000
	s_waitcnt vmcnt(40)
	v_mov_b32_e32 v80, v232
	v_mov_b32_e32 v79, v233
	v_mov_b32_e32 v78, v234
	v_mov_b32_e32 v77, v235
	v_mov_b32_e32 v105, v236
	v_mov_b32_e32 v104, v237
	v_mov_b32_e32 v103, v238
	v_mov_b32_e32 v102, v239
	v_mov_b32_e32 v101, v240
	v_mov_b32_e32 v100, v241
	v_mov_b32_e32 v99, v242
	v_mov_b32_e32 v98, v243
	v_mov_b32_e32 v81, v231
	v_mov_b32_e32 v82, v230
	v_mov_b32_e32 v92, v244
	v_mov_b32_e32 v91, v245
	v_mov_b32_e32 v90, v246
	v_mov_b32_e32 v89, v247
	v_mov_b32_e32 v83, v229
	v_mov_b32_e32 v84, v228
	v_mov_b32_e32 v1, v227
	v_mov_b32_e32 v70, v226
	v_mov_b32_e32 v88, v248
	v_mov_b32_e32 v87, v249
	v_mov_b32_e32 v86, v250
	v_mov_b32_e32 v85, v251
	v_mov_b32_e32 v71, v225
	v_mov_b32_e32 v72, v224
	v_mov_b32_e32 v73, v223
	v_mov_b32_e32 v74, v222
	v_mov_b32_e32 v75, v221
	v_mov_b32_e32 v76, v220
	s_cbranch_vccz .Lwd_exit
.Lwd_Y:
	s_add_i32 s9, s6, 0xfffffc00
	s_ashr_i32 s0, s9, 31
	s_lshr_b32 s0, s0, 25
	s_add_i32 s0, s9, s0
	s_ashr_i32 s12, s0, 7
	s_lshl_b32 s0, s12, 12
	s_sub_i32 s13, s7, s0
	s_cmpk_lt_i32 s9, 0x5200
	s_cselect_b64 s[0:1], -1, 0
	s_and_b64 vcc, s[0:1], exec
	s_add_i32 s32, s6, 0x400
	s_cmpk_lt_i32 s9, 0x4e00
	s_cselect_b32 s9, s32, s9
	s_ashr_i32 s0, s9, 31
	s_lshr_b32 s0, s0, 25
	s_add_i32 s0, s9, s0
	s_ashr_i32 s10, s0, 7
	s_lshl_b32 s0, s10, 6
	s_ashr_i32 s1, s0, 31
	s_lshl_b64 s[0:1], s[0:1], 14
	s_add_u32 s11, s60, s0
	s_addc_u32 s14, s61, s1
	s_lshl_b32 s0, s10, 12
	s_lshl_b32 s1, s9, 5
	s_sub_i32 s0, s1, s0
	s_ashr_i32 s1, s0, 31
	s_lshl_b64 s[0:1], s[0:1], 2
	s_add_u32 s10, s11, s0
	s_addc_u32 s11, s14, s1
	v_lshl_add_u64 v[108:109], s[10:11], 0, v[2:3]
	v_mad_u64_u32 v[110:111], s[18:19], v6, 1, v[108:109]
	v_mad_u64_u32 v[112:113], s[18:19], v8, 1, v[108:109]
	v_mad_u64_u32 v[114:115], s[18:19], v10, 1, v[108:109]
	v_mad_u64_u32 v[116:117], s[18:19], v12, 1, v[108:109]
	v_mad_u64_u32 v[118:119], s[18:19], v14, 1, v[108:109]
	v_mad_u64_u32 v[120:121], s[18:19], v16, 1, v[108:109]
	v_mad_u64_u32 v[122:123], s[18:19], v18, 1, v[108:109]
	v_mad_u64_u32 v[124:125], s[18:19], v20, 1, v[108:109]
	v_mad_u64_u32 v[126:127], s[18:19], v22, 1, v[108:109]
	v_mad_u64_u32 v[128:129], s[18:19], v24, 1, v[108:109]
	v_mad_u64_u32 v[130:131], s[18:19], v26, 1, v[108:109]
	v_mad_u64_u32 v[132:133], s[18:19], v28, 1, v[108:109]
	v_mad_u64_u32 v[134:135], s[18:19], v30, 1, v[108:109]
	v_mad_u64_u32 v[136:137], s[18:19], v32, 1, v[108:109]
	v_mad_u64_u32 v[138:139], s[18:19], v34, 1, v[108:109]
	v_mad_u64_u32 v[140:141], s[18:19], v36, 1, v[108:109]
	v_mad_u64_u32 v[142:143], s[18:19], v38, 1, v[108:109]
	v_mad_u64_u32 v[144:145], s[18:19], v40, 1, v[108:109]
	v_mad_u64_u32 v[146:147], s[18:19], v42, 1, v[108:109]
	v_mad_u64_u32 v[148:149], s[18:19], v44, 1, v[108:109]
	v_mad_u64_u32 v[150:151], s[18:19], v46, 1, v[108:109]
	v_mad_u64_u32 v[152:153], s[18:19], v48, 1, v[108:109]
	v_mad_u64_u32 v[154:155], s[18:19], v50, 1, v[108:109]
	v_mad_u64_u32 v[156:157], s[18:19], v52, 1, v[108:109]
	v_mad_u64_u32 v[158:159], s[18:19], v54, 1, v[108:109]
	v_mad_u64_u32 v[160:161], s[18:19], v56, 1, v[108:109]
	v_mad_u64_u32 v[162:163], s[18:19], v58, 1, v[108:109]
	v_mad_u64_u32 v[164:165], s[18:19], v60, 1, v[108:109]
	v_mad_u64_u32 v[166:167], s[18:19], v62, 1, v[108:109]
	v_mad_u64_u32 v[168:169], s[18:19], v64, 1, v[108:109]
; #define LAS __attribute__((address_space(3)))
; #define LDS_WAIT() asm volatile("s_waitcnt lgkmcnt(0)" ::: "memory")
; __device__ __forceinline__ unsigned pk2(float lo, float hi) { const f32x2c v = {lo, hi}; return __builtin_bit_cast(unsigned, __builtin_convertvector(v, bf16x2c)); }
; __device__ __forceinline__ void transpose_items_pipe(const float* W, int K, int ldw, int src0, int ncols, int blk, int mul, int add, bf16* WT, LAS float* scr, int gw, int NGW, int lane) {
;     ...
;           const int kb2 = ld / nblk, nb2 = ld - kb2 * nblk; const float* src = W + (size_t)(64 * kb2) * ldw + src0 + 32 * nb2 + (lane & 31);
; #pragma unroll
;           for (int i = 0; i < 32; ++i) nv[i] = src[(size_t)(2 * i + (lane >> 5)) * ldw]; }
;         asm volatile("" ::: "memory");
; #pragma unroll
;         for (int i = 0; i < 32; ++i) scr[(2 * i + (lane >> 5)) * 33 + (lane & 31)] = tv[i];
;         LDS_WAIT(); asm volatile("" ::: "memory");
;         const int c = lane & 7;
; #pragma unroll
;         for (int j = 0; j < 4; ++j) { const int n = (lane >> 3) + 8 * j; const LAS float* s = scr + (8 * c) * 33 + n;
;             v4u o; o.x = pk2(s[0 * 33], s[1 * 33]); o.y = pk2(s[2 * 33], s[3 * 33]); o.z = pk2(s[4 * 33], s[5 * 33]); o.w = pk2(s[6 * 33], s[7 * 33]);
;             *(v4u*)(WT + (size_t)(drow + n) * K + k0 + 8 * c) = o; }
;         LDS_WAIT(); asm volatile("" ::: "memory");
;         if (!more) break;
; #pragma unroll
;         for (int i = 0; i < 32; ++i) tv[i] = nv[i];
;         it = nit;
	v_mad_u64_u32 v[170:171], s[18:19], v66, 1, v[108:109]
	v_mad_u64_u32 v[108:109], s[18:19], v68, 1, v[108:109]
	global_load_dword v220, v[110:111], off
	global_load_dword v221, v[112:113], off
	global_load_dword v222, v[114:115], off
	global_load_dword v223, v[116:117], off
	global_load_dword v224, v[118:119], off
	global_load_dword v225, v[120:121], off
	global_load_dword v226, v[122:123], off
	global_load_dword v227, v[124:125], off
	global_load_dword v228, v[126:127], off
	global_load_dword v229, v[128:129], off
	global_load_dword v230, v[130:131], off
	global_load_dword v231, v[132:133], off
	global_load_dword v232, v[134:135], off
	global_load_dword v233, v[136:137], off
	global_load_dword v234, v[138:139], off
	global_load_dword v235, v[140:141], off
	global_load_dword v236, v[158:159], off
	global_load_dword v237, v[160:161], off
	global_load_dword v238, v[162:163], off
	global_load_dword v239, v[164:165], off
	global_load_dword v240, v[166:167], off
	global_load_dword v241, v[168:169], off
	global_load_dword v242, v[170:171], off
	global_load_dword v243, v[108:109], off
	global_load_dword v244, v[142:143], off
	global_load_dword v245, v[144:145], off
	global_load_dword v246, v[146:147], off
	global_load_dword v247, v[148:149], off
	global_load_dword v248, v[150:151], off
	global_load_dword v249, v[152:153], off
	global_load_dword v250, v[154:155], off
	global_load_dword v251, v[156:157], off
	v_add_u32_e32 v107, 0x400, v106
	v_add_u32_e32 v174, 0x800, v106
	v_add_u32_e32 v175, 0xc00, v106
	v_add_u32_e32 v176, 0x1000, v106
	v_add_u32_e32 v177, 0x1400, v106
	v_add_u32_e32 v178, 0x1800, v106
	v_add_u32_e32 v179, 0x1c00, v106
	ds_write2_b32 v106, v76, v75 offset1:66
	ds_write2_b32 v106, v74, v73 offset0:132 offset1:198
	ds_write2_b32 v107, v72, v71 offset0:8 offset1:74
	ds_write2_b32 v107, v70, v1 offset0:140 offset1:206
	ds_write2_b32 v174, v84, v83 offset0:16 offset1:82
	ds_write2_b32 v174, v82, v81 offset0:148 offset1:214
	ds_write2_b32 v175, v80, v79 offset0:24 offset1:90
	ds_write2_b32 v175, v78, v77 offset0:156 offset1:222
	ds_write2_b32 v176, v92, v91 offset0:32 offset1:98
	ds_write2_b32 v176, v90, v89 offset0:164 offset1:230
	ds_write2_b32 v177, v88, v87 offset0:40 offset1:106
	ds_write2_b32 v177, v86, v85 offset0:172 offset1:238
	ds_write2_b32 v178, v105, v104 offset0:48 offset1:114
	ds_write2_b32 v178, v103, v102 offset0:180 offset1:246
	ds_write2_b32 v179, v101, v100 offset0:56 offset1:122
	ds_write2_b32 v179, v99, v98 offset0:188 offset1:254
	s_waitcnt lgkmcnt(0)
	s_ashr_i32 s1, s13, 31
	s_lshl_b32 s0, s12, 6
	s_lshr_b32 s9, s1, 2
	ds_read2_b32 v[74:75], v94 offset0:33 offset1:41
	ds_read2_b32 v[76:77], v94 offset1:8
	ds_read2_b32 v[78:79], v94 offset0:66 offset1:74
	ds_read2_b32 v[80:81], v94 offset0:99 offset1:107
	ds_read2_b32 v[82:83], v94 offset0:132 offset1:140
	ds_read2_b32 v[84:85], v94 offset0:165 offset1:173
	ds_read2_b32 v[86:87], v94 offset0:198 offset1:206
	ds_read2_b32 v[88:89], v94 offset0:231 offset1:239
	s_ashr_i32 s1, s0, 31
	s_add_i32 s9, s13, s9
	ds_read2_b32 v[100:101], v94 offset0:49 offset1:57
	ds_read2_b32 v[102:103], v94 offset0:16 offset1:24
	ds_read2_b32 v[104:105], v94 offset0:82 offset1:90
	ds_read2_b32 v[108:109], v94 offset0:115 offset1:123
	ds_read2_b32 v[110:111], v94 offset0:148 offset1:156
	ds_read2_b32 v[112:113], v94 offset0:181 offset1:189
	ds_read2_b32 v[114:115], v94 offset0:214 offset1:222
	ds_read2_b32 v[116:117], v94 offset0:247 offset1:255
	v_lshl_add_u64 v[172:173], s[0:1], 1, v[4:5]
	s_and_b32 s0, s9, -2.0
	s_sub_i32 s0, s13, s0
	v_or_b32_e32 v1, s0, v93
	v_or_b32_e32 v70, s0, v95
	v_or_b32_e32 v71, s0, v96
	v_or_b32_e32 v72, s0, v97
	v_mad_i64_i32 v[90:91], s[0:1], v1, s8, v[172:173]
	v_mad_i64_i32 v[98:99], s[0:1], v70, s8, v[172:173]
	v_mad_i64_i32 v[118:119], s[0:1], v71, s8, v[172:173]
	v_mad_i64_i32 v[120:121], s[0:1], v72, s8, v[172:173]
	s_waitcnt lgkmcnt(14)
	v_cvt_pk_bf16_f32 v70, v76, v74
	s_waitcnt lgkmcnt(12)
	v_cvt_pk_bf16_f32 v71, v78, v80
	s_waitcnt lgkmcnt(10)
	v_cvt_pk_bf16_f32 v72, v82, v84
	s_waitcnt lgkmcnt(8)
	v_cvt_pk_bf16_f32 v73, v86, v88
	v_cvt_pk_bf16_f32 v74, v77, v75
	v_cvt_pk_bf16_f32 v75, v79, v81
	v_cvt_pk_bf16_f32 v76, v83, v85
	v_cvt_pk_bf16_f32 v77, v87, v89
	s_waitcnt lgkmcnt(6)
	v_cvt_pk_bf16_f32 v78, v102, v100
	s_waitcnt lgkmcnt(4)
	v_cvt_pk_bf16_f32 v79, v104, v108
	s_waitcnt lgkmcnt(2)
	v_cvt_pk_bf16_f32 v80, v110, v112
	s_waitcnt lgkmcnt(0)
	v_cvt_pk_bf16_f32 v81, v114, v116
	v_cvt_pk_bf16_f32 v82, v103, v101
	v_cvt_pk_bf16_f32 v83, v105, v109
	v_cvt_pk_bf16_f32 v84, v111, v113
	v_cvt_pk_bf16_f32 v85, v115, v117
	global_store_dwordx4 v[90:91], v[70:73], off
	global_store_dwordx4 v[98:99], v[74:77], off
	global_store_dwordx4 v[118:119], v[78:81], off
	global_store_dwordx4 v[120:121], v[82:85], off
	s_waitcnt lgkmcnt(0)
	s_addk_i32 s6, 0x400
	s_add_i32 s7, s7, 0x8000
	s_waitcnt vmcnt(40)
	v_mov_b32_e32 v80, v31
	v_mov_b32_e32 v79, v33
	v_mov_b32_e32 v78, v35
	v_mov_b32_e32 v77, v37
	v_mov_b32_e32 v105, v39
	v_mov_b32_e32 v104, v41
	v_mov_b32_e32 v103, v43
	v_mov_b32_e32 v102, v45
	v_mov_b32_e32 v101, v47
	v_mov_b32_e32 v100, v49
	v_mov_b32_e32 v99, v51
	v_mov_b32_e32 v98, v53
	v_mov_b32_e32 v81, v29
	v_mov_b32_e32 v82, v27
	v_mov_b32_e32 v92, v55
	v_mov_b32_e32 v91, v57
	v_mov_b32_e32 v90, v59
	v_mov_b32_e32 v89, v61
	v_mov_b32_e32 v83, v25
	v_mov_b32_e32 v84, v23
	v_mov_b32_e32 v1, v21
	v_mov_b32_e32 v70, v19
	v_mov_b32_e32 v88, v63
	v_mov_b32_e32 v87, v65
	v_mov_b32_e32 v86, v67
	v_mov_b32_e32 v85, v69
	v_mov_b32_e32 v71, v17
	v_mov_b32_e32 v72, v15
	v_mov_b32_e32 v73, v13
	v_mov_b32_e32 v74, v11
	v_mov_b32_e32 v75, v9
	v_mov_b32_e32 v76, v7
	s_cbranch_vccnz .Lwd_X
